# v16 + per-unit accumulator zeroing with 64 v_mov_b64 instead of 128 v_mov_b32 (7 GEMM phases)
# speedup vs baseline: 1.0011x; 1.0011x over previous
; #define GAS __attribute__((address_space(1)))
;     __device__ bool next(int i, Unit& u) const { if (!pg8::StaticOrder::next(i, u)) return false; if (u.pn >= 12) u.pn += 4; return true; }
;     __device__ bool next(int i, Unit& u) const { const int L = i * G + c; if (L >= 128) return false; u.pm = L; u.pn = L >> 1; u.kind = 0; return true; }
;     __device__ bool next(int i, Unit& u) const { const int L = i * G + c; if (L < n0) return a.next(L, u); if (!b.next(L - n0, u)) return false; u.kind = 1; return true; }
; template <class Epi, class Sched, bool ALIGN_EPI>
; __device__ __forceinline__ void gemm_phase(LAS unsigned char* lds, const Gemm g, const Sched& S, const Epi& E, int wave_id) {
;     ...
;         const bool has_next = S.next(ui + 1, nxt);
;         const GAS char* nA = has_next ? (const GAS char*)(nxt.kind ? g.A2 : g.A) + (size_t)nxt.pm * tsA : cA; const GAS char* nB = has_next ? (const GAS char*)(nxt.kind ? g.Bt2 : g.Bt) + (size_t)nxt.pn * tsB : cB;
;     ...
;         for (int a = 0; a < 2; ++a)
; #pragma unroll
;             for (int b = 0; b < 2; ++b)
; #pragma unroll
;                 for (int m = 0; m < 4; ++m)
; #pragma unroll
;                     for (int n = 0; n < 2; ++n) acc[a][b][m][n] = (f32x4){0.f, 0.f, 0.f, 0.f};
.LBB0_1116:
	s_ashr_i32 s47, s46, 31
	s_lshl_b64 s[52:53], s[46:47], 20
	s_cmp_eq_u32 s19, 0
	s_cselect_b32 s47, s3, s66
	s_cselect_b32 s33, s63, s67
	s_cselect_b32 s57, s64, s3
	s_cselect_b32 s60, s65, s63
	s_add_u32 s52, s47, s52
	s_addc_u32 s53, s33, s53
	s_and_b64 s[54:55], s[50:51], exec
	s_cselect_b32 s33, s53, s59
	s_cselect_b32 s47, s52, s58
	s_ashr_i32 s49, s48, 31
	s_lshl_b64 s[54:55], s[48:49], 20
	s_add_u32 s54, s57, s54
	s_addc_u32 s55, s60, s55
	s_and_b64 s[60:61], s[50:51], exec
	s_cselect_b32 s49, s55, s1
	s_cselect_b32 s57, s54, s0
	s_add_u32 s71, s0, 0x100
	s_addc_u32 s74, s1, 0
	s_add_u32 s0, s58, 0x80080
	v_mov_b64_e32 v[2:3], 0
	s_addc_u32 s1, s59, 0
	s_mov_b32 s76, -2
	v_mov_b64_e32 v[4:5], 0
	v_mov_b64_e32 v[6:7], 0
	v_mov_b64_e32 v[8:9], 0
	v_mov_b64_e32 v[18:19], 0
	v_mov_b64_e32 v[20:21], 0
	v_mov_b64_e32 v[22:23], 0
	v_mov_b64_e32 v[24:25], 0
	v_mov_b64_e32 v[34:35], 0
	v_mov_b64_e32 v[36:37], 0
	v_mov_b64_e32 v[38:39], 0
	v_mov_b64_e32 v[40:41], 0
	v_mov_b64_e32 v[50:51], 0
	v_mov_b64_e32 v[52:53], 0
	v_mov_b64_e32 v[54:55], 0
	v_mov_b64_e32 v[56:57], 0
	v_mov_b64_e32 v[10:11], 0
	v_mov_b64_e32 v[12:13], 0
	v_mov_b64_e32 v[14:15], 0
	v_mov_b64_e32 v[16:17], 0
	v_mov_b64_e32 v[26:27], 0
	v_mov_b64_e32 v[28:29], 0
	v_mov_b64_e32 v[30:31], 0
	v_mov_b64_e32 v[32:33], 0
	v_mov_b64_e32 v[42:43], 0
	v_mov_b64_e32 v[44:45], 0
	v_mov_b64_e32 v[46:47], 0
	v_mov_b64_e32 v[48:49], 0
	v_mov_b64_e32 v[58:59], 0
	v_mov_b64_e32 v[60:61], 0
	v_mov_b64_e32 v[62:63], 0
	v_mov_b64_e32 v[64:65], 0
	v_mov_b64_e32 v[66:67], 0
	v_mov_b64_e32 v[68:69], 0
	v_mov_b64_e32 v[70:71], 0
	v_mov_b64_e32 v[72:73], 0
	v_mov_b64_e32 v[82:83], 0
	v_mov_b64_e32 v[84:85], 0
	v_mov_b64_e32 v[86:87], 0
	v_mov_b64_e32 v[88:89], 0
	v_mov_b64_e32 v[98:99], 0
	v_mov_b64_e32 v[100:101], 0
	v_mov_b64_e32 v[102:103], 0
	v_mov_b64_e32 v[104:105], 0
	v_mov_b64_e32 v[114:115], 0
	v_mov_b64_e32 v[116:117], 0
	v_mov_b64_e32 v[118:119], 0
	v_mov_b64_e32 v[120:121], 0
	v_mov_b64_e32 v[74:75], 0
	v_mov_b64_e32 v[76:77], 0
	v_mov_b64_e32 v[78:79], 0
	v_mov_b64_e32 v[80:81], 0
	v_mov_b64_e32 v[90:91], 0
	v_mov_b64_e32 v[92:93], 0
	v_mov_b64_e32 v[94:95], 0
	v_mov_b64_e32 v[96:97], 0
	v_mov_b64_e32 v[106:107], 0
	v_mov_b64_e32 v[108:109], 0
	v_mov_b64_e32 v[110:111], 0
	v_mov_b64_e32 v[112:113], 0
	v_mov_b64_e32 v[122:123], 0
	v_mov_b64_e32 v[124:125], 0
	v_mov_b64_e32 v[126:127], 0
	v_mov_b64_e32 v[128:129], 0

; template <class Epi, class Sched, bool ALIGN_EPI>
; __device__ __forceinline__ void gemm_phase(LAS unsigned char* lds, const Gemm g, const Sched& S, const Epi& E, int wave_id) {
;     ...
;         for (int a = 0; a < 2; ++a)
; #pragma unroll
;             for (int b = 0; b < 2; ++b)
; #pragma unroll
;                 for (int m = 0; m < 4; ++m)
; #pragma unroll
;                     for (int n = 0; n < 2; ++n) acc[a][b][m][n] = (f32x4){0.f, 0.f, 0.f, 0.f};
.LBB0_1644:
	s_add_u32 s53, s20, 0x100
	v_mov_b64_e32 v[2:3], 0
	s_addc_u32 s54, s21, 0
	s_mov_b32 s55, -2
	v_mov_b64_e32 v[4:5], 0
	v_mov_b64_e32 v[6:7], 0
	v_mov_b64_e32 v[8:9], 0
	v_mov_b64_e32 v[10:11], 0
	v_mov_b64_e32 v[12:13], 0
	v_mov_b64_e32 v[14:15], 0
	v_mov_b64_e32 v[16:17], 0
	v_mov_b64_e32 v[18:19], 0
	v_mov_b64_e32 v[20:21], 0
	v_mov_b64_e32 v[22:23], 0
	v_mov_b64_e32 v[24:25], 0
	v_mov_b64_e32 v[26:27], 0
	v_mov_b64_e32 v[28:29], 0
	v_mov_b64_e32 v[30:31], 0
	v_mov_b64_e32 v[32:33], 0
	v_mov_b64_e32 v[66:67], 0
	v_mov_b64_e32 v[68:69], 0
	v_mov_b64_e32 v[70:71], 0
	v_mov_b64_e32 v[72:73], 0
	v_mov_b64_e32 v[74:75], 0
	v_mov_b64_e32 v[76:77], 0
	v_mov_b64_e32 v[78:79], 0
	v_mov_b64_e32 v[80:81], 0
	v_mov_b64_e32 v[82:83], 0
	v_mov_b64_e32 v[84:85], 0
	v_mov_b64_e32 v[86:87], 0
	v_mov_b64_e32 v[88:89], 0
	v_mov_b64_e32 v[90:91], 0
	v_mov_b64_e32 v[92:93], 0
	v_mov_b64_e32 v[94:95], 0
	v_mov_b64_e32 v[96:97], 0
	v_mov_b64_e32 v[34:35], 0
	v_mov_b64_e32 v[36:37], 0
	v_mov_b64_e32 v[38:39], 0
	v_mov_b64_e32 v[40:41], 0
	v_mov_b64_e32 v[42:43], 0
	v_mov_b64_e32 v[44:45], 0
	v_mov_b64_e32 v[46:47], 0
	v_mov_b64_e32 v[48:49], 0
	v_mov_b64_e32 v[50:51], 0
	v_mov_b64_e32 v[52:53], 0
	v_mov_b64_e32 v[54:55], 0
	v_mov_b64_e32 v[56:57], 0
	v_mov_b64_e32 v[58:59], 0
	v_mov_b64_e32 v[60:61], 0
	v_mov_b64_e32 v[62:63], 0
	v_mov_b64_e32 v[64:65], 0
	v_mov_b64_e32 v[98:99], 0
	v_mov_b64_e32 v[100:101], 0
	v_mov_b64_e32 v[102:103], 0
	v_mov_b64_e32 v[104:105], 0
	v_mov_b64_e32 v[106:107], 0
	v_mov_b64_e32 v[108:109], 0
	v_mov_b64_e32 v[110:111], 0
	v_mov_b64_e32 v[112:113], 0
	v_mov_b64_e32 v[122:123], 0
	v_mov_b64_e32 v[124:125], 0
	v_mov_b64_e32 v[126:127], 0
	v_mov_b64_e32 v[128:129], 0
	v_mov_b64_e32 v[138:139], 0
	v_mov_b64_e32 v[140:141], 0
	v_mov_b64_e32 v[142:143], 0
	v_mov_b64_e32 v[144:145], 0

; #define GAS __attribute__((address_space(1)))
;     __device__ bool next(int i, Unit& u) const { if (!pg8::StaticOrder::next(i, u)) return false; if (u.pn >= 12) u.pn += 4; return true; }
;     __device__ bool next(int i, Unit& u) const { const int L = i * G + c; if (L >= 128) return false; u.pm = L; u.pn = L >> 1; u.kind = 0; return true; }
;     __device__ bool next(int i, Unit& u) const { const int L = i * G + c; if (L < n0) return a.next(L, u); if (!b.next(L - n0, u)) return false; u.kind = 1; return true; }
; template <class Epi, class Sched, bool ALIGN_EPI>
; __device__ __forceinline__ void gemm_phase(LAS unsigned char* lds, const Gemm g, const Sched& S, const Epi& E, int wave_id) {
;     ...
;         const bool has_next = S.next(ui + 1, nxt);
;         const GAS char* nA = has_next ? (const GAS char*)(nxt.kind ? g.A2 : g.A) + (size_t)nxt.pm * tsA : cA; const GAS char* nB = has_next ? (const GAS char*)(nxt.kind ? g.Bt2 : g.Bt) + (size_t)nxt.pn * tsB : cB;
;     ...
;         for (int a = 0; a < 2; ++a)
; #pragma unroll
;             for (int b = 0; b < 2; ++b)
; #pragma unroll
;                 for (int m = 0; m < 4; ++m)
; #pragma unroll
;                     for (int n = 0; n < 2; ++n) acc[a][b][m][n] = (f32x4){0.f, 0.f, 0.f, 0.f};
.LBB0_1836:
	s_ashr_i32 s25, s24, 31
	s_lshl_b64 s[30:31], s[24:25], 19
	s_cmp_eq_u32 s65, 0
	s_cselect_b32 s25, s2, s8
	s_cselect_b32 s5, s3, s9
	s_cselect_b32 s37, s6, s10
	s_cselect_b32 s39, s7, s11
	s_add_u32 s30, s25, s30
	s_addc_u32 s31, s5, s31
	s_and_b64 s[34:35], s[28:29], exec
	s_cselect_b32 s5, s31, s43
	s_cselect_b32 s25, s30, s42
	s_ashr_i32 s27, s26, 31
	s_lshl_b64 s[34:35], s[26:27], 19
	s_add_u32 s34, s37, s34
	s_addc_u32 s35, s39, s35
	s_and_b64 s[44:45], s[28:29], exec
	s_cselect_b32 s27, s35, s41
	s_cselect_b32 s37, s34, s40
	s_add_u32 s39, s40, 0x100
	s_addc_u32 s66, s41, 0
	s_add_u32 s40, s42, 0x40080
	v_mov_b64_e32 v[2:3], 0
	s_addc_u32 s41, s43, 0
	s_mov_b32 s67, -2
	v_mov_b64_e32 v[4:5], 0
	v_mov_b64_e32 v[6:7], 0
	v_mov_b64_e32 v[8:9], 0
	v_mov_b64_e32 v[14:15], 0
	v_mov_b64_e32 v[16:17], 0
	v_mov_b64_e32 v[22:23], 0
	v_mov_b64_e32 v[24:25], 0
	v_mov_b64_e32 v[30:31], 0
	v_mov_b64_e32 v[32:33], 0
	v_mov_b64_e32 v[38:39], 0
	v_mov_b64_e32 v[40:41], 0
	v_mov_b64_e32 v[46:47], 0
	v_mov_b64_e32 v[48:49], 0
	v_mov_b64_e32 v[54:55], 0
	v_mov_b64_e32 v[56:57], 0
	v_mov_b64_e32 v[10:11], 0
	v_mov_b64_e32 v[12:13], 0
	v_mov_b64_e32 v[18:19], 0
	v_mov_b64_e32 v[20:21], 0
	v_mov_b64_e32 v[26:27], 0
	v_mov_b64_e32 v[28:29], 0
	v_mov_b64_e32 v[34:35], 0
	v_mov_b64_e32 v[36:37], 0
	v_mov_b64_e32 v[42:43], 0
	v_mov_b64_e32 v[44:45], 0
	v_mov_b64_e32 v[50:51], 0
	v_mov_b64_e32 v[52:53], 0
	v_mov_b64_e32 v[58:59], 0
	v_mov_b64_e32 v[60:61], 0
	v_mov_b64_e32 v[62:63], 0
	v_mov_b64_e32 v[64:65], 0
	v_mov_b64_e32 v[66:67], 0
	v_mov_b64_e32 v[68:69], 0
	v_mov_b64_e32 v[70:71], 0
	v_mov_b64_e32 v[72:73], 0
	s_waitcnt vmcnt(0)
	v_mov_b64_e32 v[78:79], 0
	v_mov_b64_e32 v[80:81], 0
	v_mov_b64_e32 v[86:87], 0
	v_mov_b64_e32 v[88:89], 0
	v_mov_b64_e32 v[94:95], 0
	v_mov_b64_e32 v[96:97], 0
	v_mov_b64_e32 v[102:103], 0
	v_mov_b64_e32 v[104:105], 0
	v_mov_b64_e32 v[110:111], 0
	v_mov_b64_e32 v[112:113], 0
	v_mov_b64_e32 v[118:119], 0
	v_mov_b64_e32 v[120:121], 0
	v_mov_b64_e32 v[74:75], 0
	v_mov_b64_e32 v[76:77], 0
	v_mov_b64_e32 v[82:83], 0
	v_mov_b64_e32 v[84:85], 0
	v_mov_b64_e32 v[90:91], 0
	v_mov_b64_e32 v[92:93], 0
	v_mov_b64_e32 v[98:99], 0
	v_mov_b64_e32 v[100:101], 0
	v_mov_b64_e32 v[106:107], 0
	v_mov_b64_e32 v[108:109], 0
	v_mov_b64_e32 v[114:115], 0
	v_mov_b64_e32 v[116:117], 0
	v_mov_b64_e32 v[122:123], 0
	v_mov_b64_e32 v[124:125], 0
	v_mov_b64_e32 v[126:127], 0
	v_mov_b64_e32 v[128:129], 0

; #define GAS __attribute__((address_space(1)))
;     __device__ bool next(int i, Unit& u) const { if (!pg8::StaticOrder::next(i, u)) return false; if (u.pn >= 12) u.pn += 4; return true; }
;     __device__ bool next(int i, Unit& u) const { const int L = i * G + c; if (L >= 128) return false; u.pm = L; u.pn = L >> 1; u.kind = 0; return true; }
;     __device__ bool next(int i, Unit& u) const { const int L = i * G + c; if (L < n0) return a.next(L, u); if (!b.next(L - n0, u)) return false; u.kind = 1; return true; }
; template <class Epi, class Sched, bool ALIGN_EPI>
; __device__ __forceinline__ void gemm_phase(LAS unsigned char* lds, const Gemm g, const Sched& S, const Epi& E, int wave_id) {
;     ...
;         const bool has_next = S.next(ui + 1, nxt);
;         const GAS char* nA = has_next ? (const GAS char*)(nxt.kind ? g.A2 : g.A) + (size_t)nxt.pm * tsA : cA; const GAS char* nB = has_next ? (const GAS char*)(nxt.kind ? g.Bt2 : g.Bt) + (size_t)nxt.pn * tsB : cB;
;     ...
;         for (int a = 0; a < 2; ++a)
; #pragma unroll
;             for (int b = 0; b < 2; ++b)
; #pragma unroll
;                 for (int m = 0; m < 4; ++m)
; #pragma unroll
;                     for (int n = 0; n < 2; ++n) acc[a][b][m][n] = (f32x4){0.f, 0.f, 0.f, 0.f};
.LBB0_2564:
	s_ashr_i32 s19, s18, 31
	s_lshl_b64 s[20:21], s[18:19], 19
	s_add_u32 s20, s36, s20
	s_addc_u32 s21, s37, s21
	s_and_b64 s[22:23], s[0:1], exec
	s_cselect_b32 s19, s21, s29
	s_cselect_b32 s33, s20, s28
	s_ashr_i32 s17, s16, 31
	s_lshl_b64 s[22:23], s[16:17], 19
	s_add_u32 s22, s38, s22
	s_addc_u32 s23, s39, s23
	s_and_b64 s[30:31], s[0:1], exec
	s_cselect_b32 s17, s23, s27
	s_cselect_b32 s57, s22, s26
	s_add_u32 s58, s26, 0x100
	s_addc_u32 s59, s27, 0
	s_add_u32 s26, s28, 0x40080
	v_mov_b64_e32 v[2:3], 0
	s_addc_u32 s27, s29, 0
	s_mov_b32 s60, -2
	v_mov_b64_e32 v[4:5], 0
	v_mov_b64_e32 v[6:7], 0
	v_mov_b64_e32 v[8:9], 0
	v_mov_b64_e32 v[18:19], 0
	v_mov_b64_e32 v[20:21], 0
	v_mov_b64_e32 v[22:23], 0
	v_mov_b64_e32 v[24:25], 0
	v_mov_b64_e32 v[34:35], 0
	v_mov_b64_e32 v[36:37], 0
	v_mov_b64_e32 v[38:39], 0
	v_mov_b64_e32 v[40:41], 0
	v_mov_b64_e32 v[50:51], 0
	v_mov_b64_e32 v[52:53], 0
	v_mov_b64_e32 v[54:55], 0
	v_mov_b64_e32 v[56:57], 0
	v_mov_b64_e32 v[10:11], 0
	v_mov_b64_e32 v[12:13], 0
	v_mov_b64_e32 v[14:15], 0
	v_mov_b64_e32 v[16:17], 0
	v_mov_b64_e32 v[26:27], 0
	v_mov_b64_e32 v[28:29], 0
	v_mov_b64_e32 v[30:31], 0
	v_mov_b64_e32 v[32:33], 0
	v_mov_b64_e32 v[42:43], 0
	v_mov_b64_e32 v[44:45], 0
	v_mov_b64_e32 v[46:47], 0
	v_mov_b64_e32 v[48:49], 0
	v_mov_b64_e32 v[58:59], 0
	v_mov_b64_e32 v[60:61], 0
	v_mov_b64_e32 v[62:63], 0
	v_mov_b64_e32 v[64:65], 0
	v_mov_b64_e32 v[66:67], 0
	v_mov_b64_e32 v[68:69], 0
	v_mov_b64_e32 v[70:71], 0
	v_mov_b64_e32 v[72:73], 0
	v_mov_b64_e32 v[82:83], 0
	v_mov_b64_e32 v[84:85], 0
	v_mov_b64_e32 v[86:87], 0
	v_mov_b64_e32 v[88:89], 0
	v_mov_b64_e32 v[98:99], 0
	v_mov_b64_e32 v[100:101], 0
	v_mov_b64_e32 v[102:103], 0
	v_mov_b64_e32 v[104:105], 0
	v_mov_b64_e32 v[114:115], 0
	v_mov_b64_e32 v[116:117], 0
	v_mov_b64_e32 v[118:119], 0
	v_mov_b64_e32 v[120:121], 0
	v_mov_b64_e32 v[74:75], 0
	v_mov_b64_e32 v[76:77], 0
	v_mov_b64_e32 v[78:79], 0
	v_mov_b64_e32 v[80:81], 0
	v_mov_b64_e32 v[90:91], 0
	v_mov_b64_e32 v[92:93], 0
	v_mov_b64_e32 v[94:95], 0
	v_mov_b64_e32 v[96:97], 0
	v_mov_b64_e32 v[106:107], 0
	v_mov_b64_e32 v[108:109], 0
	v_mov_b64_e32 v[110:111], 0
	v_mov_b64_e32 v[112:113], 0
	v_mov_b64_e32 v[122:123], 0
	v_mov_b64_e32 v[124:125], 0
	v_mov_b64_e32 v[126:127], 0
	v_mov_b64_e32 v[128:129], 0

; #define GAS __attribute__((address_space(1)))
;     __device__ bool next(int i, Unit& u) const { if (!pg8::StaticOrder::next(i, u)) return false; if (u.pn >= 12) u.pn += 4; return true; }
;     __device__ bool next(int i, Unit& u) const { const int L = i * G + c; if (L >= 128) return false; u.pm = L; u.pn = L >> 1; u.kind = 0; return true; }
;     __device__ bool next(int i, Unit& u) const { const int L = i * G + c; if (L < n0) return a.next(L, u); if (!b.next(L - n0, u)) return false; u.kind = 1; return true; }
; template <class Epi, class Sched, bool ALIGN_EPI>
; __device__ __forceinline__ void gemm_phase(LAS unsigned char* lds, const Gemm g, const Sched& S, const Epi& E, int wave_id) {
;     ...
;         const bool has_next = S.next(ui + 1, nxt);
;         const GAS char* nA = has_next ? (const GAS char*)(nxt.kind ? g.A2 : g.A) + (size_t)nxt.pm * tsA : cA; const GAS char* nB = has_next ? (const GAS char*)(nxt.kind ? g.Bt2 : g.Bt) + (size_t)nxt.pn * tsB : cB;
;     ...
;         for (int a = 0; a < 2; ++a)
; #pragma unroll
;             for (int b = 0; b < 2; ++b)
; #pragma unroll
;                 for (int m = 0; m < 4; ++m)
; #pragma unroll
;                     for (int n = 0; n < 2; ++n) acc[a][b][m][n] = (f32x4){0.f, 0.f, 0.f, 0.f};
.LBB0_2619:
	s_ashr_i32 s29, s28, 31
	s_lshl_b64 s[30:31], s[28:29], 20
	s_add_u32 s30, s44, s30
	s_addc_u32 s31, s45, s31
	s_and_b64 s[34:35], s[2:3], exec
	s_cselect_b32 s1, s31, s39
	s_cselect_b32 s5, s30, s38
	s_ashr_i32 s27, s26, 31
	s_lshl_b64 s[34:35], s[26:27], 20
	s_add_u32 s34, s46, s34
	s_addc_u32 s35, s47, s35
	s_and_b64 s[40:41], s[2:3], exec
	s_cselect_b32 s7, s35, s37
	s_cselect_b32 s27, s34, s36
	s_add_u32 s29, s36, 0x100
	s_addc_u32 s33, s37, 0
	s_add_u32 s36, s38, 0x80080
	v_mov_b64_e32 v[2:3], 0
	s_addc_u32 s37, s39, 0
	s_mov_b32 s65, -2
	v_mov_b64_e32 v[4:5], 0
	v_mov_b64_e32 v[6:7], 0
	v_mov_b64_e32 v[8:9], 0
	v_mov_b64_e32 v[18:19], 0
	v_mov_b64_e32 v[20:21], 0
	v_mov_b64_e32 v[22:23], 0
	v_mov_b64_e32 v[24:25], 0
	v_mov_b64_e32 v[66:67], 0
	v_mov_b64_e32 v[68:69], 0
	v_mov_b64_e32 v[70:71], 0
	v_mov_b64_e32 v[72:73], 0
	v_mov_b64_e32 v[86:87], 0
	v_mov_b64_e32 v[88:89], 0
	v_mov_b64_e32 v[90:91], 0
	v_mov_b64_e32 v[92:93], 0
	v_mov_b64_e32 v[10:11], 0
	v_mov_b64_e32 v[12:13], 0
	v_mov_b64_e32 v[14:15], 0
	v_mov_b64_e32 v[16:17], 0
	v_mov_b64_e32 v[26:27], 0
	v_mov_b64_e32 v[28:29], 0
	v_mov_b64_e32 v[30:31], 0
	v_mov_b64_e32 v[32:33], 0
	v_mov_b64_e32 v[74:75], 0
	v_mov_b64_e32 v[76:77], 0
	v_mov_b64_e32 v[78:79], 0
	v_mov_b64_e32 v[80:81], 0
	v_mov_b64_e32 v[98:99], 0
	v_mov_b64_e32 v[100:101], 0
	v_mov_b64_e32 v[102:103], 0
	v_mov_b64_e32 v[104:105], 0
	v_mov_b64_e32 v[106:107], 0
	v_mov_b64_e32 v[108:109], 0
	v_mov_b64_e32 v[110:111], 0
	v_mov_b64_e32 v[112:113], 0
	v_mov_b64_e32 v[122:123], 0
	v_mov_b64_e32 v[124:125], 0
	v_mov_b64_e32 v[126:127], 0
	v_mov_b64_e32 v[128:129], 0
	v_mov_b64_e32 v[138:139], 0
	v_mov_b64_e32 v[140:141], 0
	v_mov_b64_e32 v[142:143], 0
	v_mov_b64_e32 v[144:145], 0
	v_mov_b64_e32 v[154:155], 0
	v_mov_b64_e32 v[156:157], 0
	v_mov_b64_e32 v[158:159], 0
	v_mov_b64_e32 v[160:161], 0
	v_mov_b64_e32 v[114:115], 0
	v_mov_b64_e32 v[116:117], 0
	v_mov_b64_e32 v[118:119], 0
	v_mov_b64_e32 v[120:121], 0
	v_mov_b64_e32 v[130:131], 0
	v_mov_b64_e32 v[132:133], 0
	v_mov_b64_e32 v[134:135], 0
	v_mov_b64_e32 v[136:137], 0
	v_mov_b64_e32 v[146:147], 0
	v_mov_b64_e32 v[148:149], 0
	v_mov_b64_e32 v[150:151], 0
	v_mov_b64_e32 v[152:153], 0
	v_mov_b64_e32 v[162:163], 0
	v_mov_b64_e32 v[164:165], 0
	v_mov_b64_e32 v[166:167], 0
	v_mov_b64_e32 v[168:169], 0

; #define GAS __attribute__((address_space(1)))
;     __device__ bool next(int i, Unit& u) const { if (!pg8::StaticOrder::next(i, u)) return false; if (u.pn >= 12) u.pn += 4; return true; }
;     __device__ bool next(int i, Unit& u) const { const int L = i * G + c; if (L >= 128) return false; u.pm = L; u.pn = L >> 1; u.kind = 0; return true; }
;     __device__ bool next(int i, Unit& u) const { const int L = i * G + c; if (L < n0) return a.next(L, u); if (!b.next(L - n0, u)) return false; u.kind = 1; return true; }
; template <class Epi, class Sched, bool ALIGN_EPI>
; __device__ __forceinline__ void gemm_phase(LAS unsigned char* lds, const Gemm g, const Sched& S, const Epi& E, int wave_id) {
;     ...
;         const bool has_next = S.next(ui + 1, nxt);
;         const GAS char* nA = has_next ? (const GAS char*)(nxt.kind ? g.A2 : g.A) + (size_t)nxt.pm * tsA : cA; const GAS char* nB = has_next ? (const GAS char*)(nxt.kind ? g.Bt2 : g.Bt) + (size_t)nxt.pn * tsB : cB;
;     ...
;         for (int a = 0; a < 2; ++a)
; #pragma unroll
;             for (int b = 0; b < 2; ++b)
; #pragma unroll
;                 for (int m = 0; m < 4; ++m)
; #pragma unroll
;                     for (int n = 0; n < 2; ++n) acc[a][b][m][n] = (f32x4){0.f, 0.f, 0.f, 0.f};
.LBB0_2873:
	s_ashr_i32 s21, s20, 31
	s_lshl_b64 s[24:25], s[20:21], 20
	s_add_u32 s24, s38, s24
	s_addc_u32 s25, s39, s25
	s_and_b64 s[2:3], s[2:3], exec
	s_cselect_b32 s21, s25, s29
	s_cselect_b32 s27, s24, s28
	s_add_u32 s33, s28, 0x100
	s_addc_u32 s66, s29, 0
	s_add_u32 s2, s30, 0x80080
	v_mov_b64_e32 v[2:3], 0
	s_addc_u32 s3, s31, 0
	s_mov_b32 s67, -2
	v_mov_b64_e32 v[4:5], 0
	v_mov_b64_e32 v[6:7], 0
	v_mov_b64_e32 v[8:9], 0
	v_mov_b64_e32 v[22:23], 0
	v_mov_b64_e32 v[24:25], 0
	v_mov_b64_e32 v[26:27], 0
	v_mov_b64_e32 v[28:29], 0
	v_mov_b64_e32 v[42:43], 0
	v_mov_b64_e32 v[44:45], 0
	v_mov_b64_e32 v[46:47], 0
	v_mov_b64_e32 v[48:49], 0
	v_mov_b64_e32 v[66:67], 0
	v_mov_b64_e32 v[68:69], 0
	v_mov_b64_e32 v[74:75], 0
	v_mov_b64_e32 v[76:77], 0
	v_mov_b64_e32 v[10:11], 0
	v_mov_b64_e32 v[12:13], 0
	v_mov_b64_e32 v[14:15], 0
	v_mov_b64_e32 v[16:17], 0
	v_mov_b64_e32 v[34:35], 0
	v_mov_b64_e32 v[36:37], 0
	v_mov_b64_e32 v[38:39], 0
	v_mov_b64_e32 v[40:41], 0
	v_mov_b64_e32 v[54:55], 0
	v_mov_b64_e32 v[56:57], 0
	v_mov_b64_e32 v[58:59], 0
	v_mov_b64_e32 v[60:61], 0
	v_mov_b64_e32 v[70:71], 0
	v_mov_b64_e32 v[72:73], 0
	v_mov_b64_e32 v[84:85], 0
	v_mov_b64_e32 v[86:87], 0
	v_mov_b64_e32 v[96:97], 0
	v_mov_b64_e32 v[98:99], 0
	v_mov_b64_e32 v[100:101], 0
	v_mov_b64_e32 v[102:103], 0
	v_mov_b64_e32 v[148:149], 0
	v_mov_b64_e32 v[150:151], 0
	v_mov_b64_e32 v[152:153], 0
	v_mov_b64_e32 v[154:155], 0
	v_mov_b64_e32 v[92:93], 0
	v_mov_b64_e32 v[94:95], 0
	v_mov_b64_e32 v[168:169], 0
	v_mov_b64_e32 v[170:171], 0
	v_mov_b64_e32 v[62:63], 0
	v_mov_b64_e32 v[64:65], 0
	v_mov_b64_e32 v[160:161], 0
	v_mov_b64_e32 v[162:163], 0
	v_mov_b64_e32 v[104:105], 0
	v_mov_b64_e32 v[106:107], 0
	v_mov_b64_e32 v[124:125], 0
	v_mov_b64_e32 v[126:127], 0
	v_mov_b64_e32 v[78:79], 0
	v_mov_b64_e32 v[80:81], 0
	v_mov_b64_e32 v[156:157], 0
	v_mov_b64_e32 v[158:159], 0
	v_mov_b64_e32 v[50:51], 0
	v_mov_b64_e32 v[52:53], 0
	v_mov_b64_e32 v[172:173], 0
	v_mov_b64_e32 v[174:175], 0
	v_mov_b64_e32 v[30:31], 0
	v_mov_b64_e32 v[32:33], 0
	v_mov_b64_e32 v[176:177], 0
	v_mov_b64_e32 v[178:179], 0

; template <class Epi, class Sched, bool ALIGN_EPI>
; __device__ __forceinline__ void gemm_phase(LAS unsigned char* lds, const Gemm g, const Sched& S, const Epi& E, int wave_id) {
;     ...
;         for (int a = 0; a < 2; ++a)
; #pragma unroll
;             for (int b = 0; b < 2; ++b)
; #pragma unroll
;                 for (int m = 0; m < 4; ++m)
; #pragma unroll
;                     for (int n = 0; n < 2; ++n) acc[a][b][m][n] = (f32x4){0.f, 0.f, 0.f, 0.f};
.LBB0_3680:
	s_add_u32 s61, s30, 0x100
	v_mov_b64_e32 v[2:3], 0
	s_addc_u32 s62, s31, 0
	s_mov_b32 s63, -2
	v_mov_b64_e32 v[4:5], 0
	v_mov_b64_e32 v[6:7], 0
	v_mov_b64_e32 v[8:9], 0
	v_mov_b64_e32 v[18:19], 0
	v_mov_b64_e32 v[20:21], 0
	s_waitcnt vmcnt(0)
	v_mov_b64_e32 v[22:23], 0
	v_mov_b64_e32 v[24:25], 0
	v_mov_b64_e32 v[66:67], 0
	v_mov_b64_e32 v[68:69], 0
	v_mov_b64_e32 v[70:71], 0
	v_mov_b64_e32 v[72:73], 0
	v_mov_b64_e32 v[82:83], 0
	v_mov_b64_e32 v[84:85], 0
	v_mov_b64_e32 v[86:87], 0
	v_mov_b64_e32 v[88:89], 0
	v_mov_b64_e32 v[10:11], 0
	v_mov_b64_e32 v[12:13], 0
	v_mov_b64_e32 v[14:15], 0
	v_mov_b64_e32 v[16:17], 0
	v_mov_b64_e32 v[26:27], 0
	v_mov_b64_e32 v[28:29], 0
	v_mov_b64_e32 v[30:31], 0
	v_mov_b64_e32 v[32:33], 0
	v_mov_b64_e32 v[74:75], 0
	v_mov_b64_e32 v[76:77], 0
	v_mov_b64_e32 v[78:79], 0
	v_mov_b64_e32 v[80:81], 0
	v_mov_b64_e32 v[90:91], 0
	v_mov_b64_e32 v[92:93], 0
	v_mov_b64_e32 v[94:95], 0
	v_mov_b64_e32 v[96:97], 0
	v_mov_b64_e32 v[98:99], 0
	v_mov_b64_e32 v[100:101], 0
	v_mov_b64_e32 v[102:103], 0
	v_mov_b64_e32 v[104:105], 0
	v_mov_b64_e32 v[114:115], 0
	v_mov_b64_e32 v[116:117], 0
	v_mov_b64_e32 v[118:119], 0
	v_mov_b64_e32 v[120:121], 0
	v_mov_b64_e32 v[130:131], 0
	v_mov_b64_e32 v[132:133], 0
	v_mov_b64_e32 v[134:135], 0
	v_mov_b64_e32 v[136:137], 0
	v_mov_b64_e32 v[146:147], 0
	v_mov_b64_e32 v[148:149], 0
	v_mov_b64_e32 v[150:151], 0
	v_mov_b64_e32 v[152:153], 0
	v_mov_b64_e32 v[106:107], 0
	v_mov_b64_e32 v[108:109], 0
	v_mov_b64_e32 v[110:111], 0
	v_mov_b64_e32 v[112:113], 0
	v_mov_b64_e32 v[122:123], 0
	v_mov_b64_e32 v[124:125], 0
	v_mov_b64_e32 v[126:127], 0
	v_mov_b64_e32 v[128:129], 0
	v_mov_b64_e32 v[138:139], 0
	v_mov_b64_e32 v[140:141], 0
	v_mov_b64_e32 v[142:143], 0
	v_mov_b64_e32 v[144:145], 0
	v_mov_b64_e32 v[154:155], 0
	v_mov_b64_e32 v[156:157], 0
	v_mov_b64_e32 v[158:159], 0
	v_mov_b64_e32 v[160:161], 0
